# v60 plus no grid rendezvous after the last chunk's down GEMM (kernel ends there)
# baseline (speedup 1.0000x reference)
.LBB0_1360:
	v_mbcnt_lo_u32_b32 v0, -1, 0
	v_mbcnt_hi_u32_b32 v0, -1, v0
	s_waitcnt vmcnt(0)
	v_readlane_b32 s0, v253, 11
	s_barrier
	s_nop 0
	v_cmp_eq_u32_e32 vcc, s0, v0
	s_bitcmp1_b32 s83, 0
	s_cselect_b64 vcc, vcc, 0
	s_cmp_lg_u32 s83, 5
	s_cselect_b64 vcc, vcc, 0
	s_and_saveexec_b64 s[0:1], vcc
	s_cbranch_execnz .LBB0_1361
	s_getpc_b64 s[98:99]
